# mixers queue: attention items claim the next item index (global atomic) when their key loop ends, so the ~2us round trip overlaps the last tile and the output epilogue instead of sitting between items
# baseline (speedup 1.0000x reference)
_Z14fwd_megakernel6Params:
	v_and_b32_e32 v163, 0x3ff, v0
	v_writelane_b32 v254, s2, 0
	s_add_u32 s2, s0, 0x120
	s_addc_u32 s3, s1, 0
	v_writelane_b32 v254, s2, 1
	v_and_b32_e32 v0, 0x3fffffff, v0
	v_mbcnt_lo_u32_b32 v203, -1, 0
	v_writelane_b32 v254, s3, 2
	v_writelane_b32 v254, s0, 3
	v_mbcnt_hi_u32_b32 v204, -1, v203
	v_and_b32_e32 v205, 64, v204
	v_writelane_b32 v254, s1, 4
	s_load_dword s0, s[0:1], 0x120
	s_mov_b32 s1, 0
	s_movk_i32 s33, 0x6000
	v_mov_b32_e32 v1, 0
	v_mov_b32_e32 v162, 0x358637bd
	s_waitcnt lgkmcnt(0)
	v_writelane_b32 v254, s0, 5
	s_cmp_eq_u32 s0, 0x100
	s_cselect_b32 s2, 1, 0
	v_writelane_b32 v255, s2, 41
	s_mov_b32 s2, 0
	v_writelane_b32 v255, s2, 51
	s_add_i32 s0, 0, 0x23fc0
	v_writelane_b32 v254, s0, 6
	s_add_i32 s0, 0, 0x19800
	v_writelane_b32 v254, s0, 7
	s_add_i32 s0, 0, 0x22400
	v_writelane_b32 v254, s0, 8
	s_add_i32 s0, 0, 0x22200
	v_writelane_b32 v254, s0, 9
	s_add_i32 s0, 0, 0x22000
	v_writelane_b32 v254, s0, 10
	s_add_i32 s0, 0, 0x11000
	v_writelane_b32 v254, s0, 11
	s_add_i32 s0, 0, 0x8800
	v_writelane_b32 v254, s0, 12
	s_add_i32 s0, 0, 0x225fc
	v_writelane_b32 v254, s0, 13
	s_add_i32 s0, 0, 0x221fc
	v_writelane_b32 v254, s0, 14
	s_add_i32 s0, 0, 0x23fe0
	v_writelane_b32 v254, s0, 15
	s_add_i32 s0, 0, 0x23fe4
	v_writelane_b32 v254, s0, 16
	s_mov_b32 s0, 0
	v_writelane_b32 v254, s0, 17
	v_writelane_b32 v254, s0, 18
	v_writelane_b32 v254, s0, 19
	s_mov_b32 s94, 0x30000
	v_mov_b32_e32 v171, 1
	v_writelane_b32 v254, s1, 20
	v_cmp_eq_u32_e64 s[0:1], 0, v0
	v_mov_b32_e32 v202, 0x2000
	v_add_u32_e32 v206, 64, v205
	v_writelane_b32 v254, s0, 21
	v_xor_b32_e32 v207, 32, v204
	v_xor_b32_e32 v208, 16, v204
	v_writelane_b32 v254, s1, 22
	s_mov_b64 s[0:1], 0
	v_writelane_b32 v254, s0, 23
	v_xor_b32_e32 v209, 8, v204
	v_xor_b32_e32 v220, 4, v204
	v_xor_b32_e32 v217, 2, v204
	v_xor_b32_e32 v212, 1, v204
	v_mov_b32_e32 v213, 0x7ff
	v_mov_b32_e32 v214, 0xff
	v_mov_b32_e32 v215, 0xffffff03
	v_mov_b64_e32 v[164:165], 0x17f
	v_mov_b64_e32 v[166:167], 0x180
	v_mov_b32_e32 v168, 0xff800000
	v_mov_b32_e32 v216, 0x800
	v_mov_b32_e32 v170, 0x3ecc95a3
	v_mov_b32_e32 v218, 0x7f800000
	v_mov_b32_e32 v219, 0x7fc00000
	v_mov_b32_e32 v221, 0x100
	v_mov_b32_e32 v222, 0x3f549a78
	v_mov_b32_e32 v223, 0x3fd49a78
	v_mov_b32_e32 v224, 0x42800000
	v_not_b32_e32 v225, 63
	v_not_b32_e32 v226, 31
	v_mov_b32_e32 v227, 0x6000
	v_mov_b32_e32 v228, 0x5000
	s_mov_b32 s95, 0x48000
	v_writelane_b32 v254, s1, 24
	s_mov_b64 s[92:93], 0x80
	s_branch .LBB0_3

.LBB0_542:
	v_mov_b32_e32 v0, v163
	s_barrier
	s_nop 0
	v_cmp_eq_u32_e32 vcc, 0, v0
	s_and_saveexec_b64 s[4:5], vcc
	s_cbranch_execz .LBB0_546
	v_readlane_b32 s98, v255, 51
	s_cmp_eq_u32 s98, 0
	s_cbranch_scc1 .Lqp_orig
	s_waitcnt vmcnt(0)
	v_readlane_b32 s0, v255, 50
	s_mov_b32 s98, 0
	v_writelane_b32 v255, s98, 51
	s_branch .Lqp_have
.Lqp_orig:
	s_mov_b64 s[8:9], exec
	v_mbcnt_lo_u32_b32 v0, s8, 0
	v_mbcnt_hi_u32_b32 v0, s9, v0
	v_cmp_eq_u32_e32 vcc, 0, v0
	s_and_saveexec_b64 s[6:7], vcc
	s_cbranch_execz .LBB0_545
	s_bcnt1_i32_b64 s0, s[8:9]
	v_mov_b32_e32 v2, s0
	v_readlane_b32 s0, v254, 40
	v_readlane_b32 s1, v254, 41
	s_nop 4
	global_atomic_add v2, v1, v2, s[0:1] offset:256 sc0

.Lqp_have:
	s_nop 1
	v_add_u32_e32 v0, s0, v0
	v_readlane_b32 s0, v254, 6
	s_nop 1
	v_mov_b32_e32 v2, s0
	ds_write_b32 v2, v0

.LBB0_575:
	v_add3_u32 v70, s12, v156, v157
	s_waitcnt vmcnt(0)
	ds_write_b128 v70, v[66:69]
	v_readfirstlane_b32 s98, v163
	s_cmp_lg_u32 s98, 0
	s_cbranch_scc1 .Lqpf_skip0
	v_readlane_b32 s98, v254, 40
	v_readlane_b32 s99, v254, 41
	s_mov_b32 exec_lo, 0
	s_mov_b32 exec_hi, 0x40000
	s_nop 4
	global_atomic_add v255, v1, v171, s[98:99] offset:256 sc0
	s_mov_b64 exec, -1
	s_mov_b32 s98, 1
	v_writelane_b32 v255, s98, 51
.Lqpf_skip0:
	s_and_saveexec_b64 s[8:9], s[4:5]
	s_cbranch_execz .LBB0_577
	s_mov_b32 s4, 0x1000504
	v_add3_u32 v70, s12, v154, v155
	s_mov_b32 s5, 0x3020706
	v_perm_b32 v66, v54, v50, s4
	v_perm_b32 v67, v58, v62, s4
	v_perm_b32 v68, v54, v50, s5
	v_perm_b32 v69, v58, v62, s5
	v_add_u32_e32 v58, 0x2000, v70
	ds_write2_b64 v58, v[66:67], v[68:69] offset0:128 offset1:146
	v_perm_b32 v66, v55, v51, s4
	v_perm_b32 v67, v59, v63, s4
	v_perm_b32 v50, v55, v51, s5
	v_perm_b32 v51, v59, v63, s5
	ds_write2_b64 v58, v[66:67], v[50:51] offset0:164 offset1:182
	v_perm_b32 v50, v56, v52, s4
	v_perm_b32 v51, v60, v64, s4
	v_perm_b32 v54, v56, v52, s5
	v_perm_b32 v55, v60, v64, s5
	ds_write2_b64 v58, v[50:51], v[54:55] offset0:200 offset1:218
	v_perm_b32 v50, v57, v53, s4
	v_perm_b32 v51, v61, v65, s4
	v_perm_b32 v52, v57, v53, s5
	v_perm_b32 v53, v61, v65, s5
	ds_write2_b64 v58, v[50:51], v[52:53] offset0:236 offset1:254

.LBB0_628:
	v_add3_u32 v0, s14, v190, v191
	s_waitcnt vmcnt(0)
	ds_write_b128 v0, v[78:81]
	v_readfirstlane_b32 s98, v163
	s_cmp_lg_u32 s98, 0
	s_cbranch_scc1 .Lqpf_skip1
	v_readlane_b32 s98, v254, 40
	v_readlane_b32 s99, v254, 41
	s_mov_b32 exec_lo, 0
	s_mov_b32 exec_hi, 0x40000
	s_nop 4
	global_atomic_add v255, v1, v171, s[98:99] offset:256 sc0
	s_mov_b64 exec, -1
	s_mov_b32 s98, 1
	v_writelane_b32 v255, s98, 51
.Lqpf_skip1:
	s_and_saveexec_b64 s[8:9], s[4:5]
	v_add3_u32 v0, s14, v188, v189
	ds_write_b128 v0, v[74:77]
	s_or_b64 exec, exec, s[8:9]
	s_and_saveexec_b64 s[4:5], s[6:7]
	s_cbranch_execz .LBB0_632
	s_mov_b32 s0, 0x1000504
	v_add3_u32 v0, s14, v192, v193
	s_mov_b32 s1, 0x3020706
	v_perm_b32 v74, v58, v66, s0
	v_perm_b32 v75, v62, v70, s0
	v_perm_b32 v76, v58, v66, s1
	v_perm_b32 v77, v62, v70, s1
	v_add_u32_e32 v0, 0x3000, v0
	ds_write2_b64 v0, v[74:75], v[76:77] offset0:128 offset1:146
	v_perm_b32 v74, v59, v67, s0
	v_perm_b32 v75, v63, v71, s0
	v_perm_b32 v58, v59, v67, s1
	v_perm_b32 v59, v63, v71, s1
	ds_write2_b64 v0, v[74:75], v[58:59] offset0:164 offset1:182
	v_perm_b32 v58, v60, v68, s0
	v_perm_b32 v59, v64, v72, s0
	v_perm_b32 v62, v60, v68, s1
	v_perm_b32 v63, v64, v72, s1
	ds_write2_b64 v0, v[58:59], v[62:63] offset0:200 offset1:218
	v_perm_b32 v58, v61, v69, s0
	v_perm_b32 v59, v65, v73, s0
	v_perm_b32 v60, v61, v69, s1
	v_perm_b32 v61, v65, v73, s1
	ds_write2_b64 v0, v[58:59], v[60:61] offset0:236 offset1:254
